# speedup vs baseline: 1.0143x; 1.0143x over previous
; __device__ __forceinline__ u16 f2bf(float f) { return (u16)(cvtpk(f, f) & 0xffffu); }
; __device__ __forceinline__ float bf2f(u16 v) { return __uint_as_float(((unsigned)v) << 16); }
; __device__ __forceinline__ int crow(int r, int hi) { return (r & 3) + 8 * (r >> 2) + 4 * hi; }
; template <int MODE>
; __device__ __forceinline__ void attn_item(const Params& P, int b, int h, int qb, char* lds) {
;     ...
; #pragma unroll
;   for (int r = 0; r < 16; ++r) {
;     const float rl = __builtin_amdgcn_rcpf(ol[r]);
;     const size_t rowoff = (size_t)(b * SEQ + q0 + crow(r, hi)) * DM + h * 128;
; #pragma unroll
;     for (int d0 = 0; d0 < 4; ++d0) {
;       const size_t idx = rowoff + d0 * 32 + r32;
;       const float v = o[d0][r] * rl * bf2f(P_gate[idx]);
;       P_og[idx] = f2bf(v);
;     }
;   }
.LBB0_680:
	s_setprio 0
	s_add_i32 s56, s56, s49
	v_or_b32_e32 v4, s56, v170
	s_lshl_b32 s0, s33, 7
	v_or_b32_e32 v2, s0, v169
	v_lshlrev_b32_e32 v4, 12, v4
	v_add_lshl_u32 v212, v4, v2, 1
	v_add_u32_e32 v213, 0x2000, v212
	v_add_u32_e32 v214, 0x4000, v212
	v_add_u32_e32 v215, 0x6000, v212
	v_add_u32_e32 v216, 0x10000, v212
	v_add_u32_e32 v217, 0x12000, v212
	v_add_u32_e32 v218, 0x14000, v212
	v_add_u32_e32 v219, 0x16000, v212
	v_add_u32_e32 v220, 0x20000, v212
	v_add_u32_e32 v221, 0x22000, v212
	v_add_u32_e32 v222, 0x24000, v212
	v_add_u32_e32 v223, 0x26000, v212
	v_add_u32_e32 v224, 0x30000, v212
	v_add_u32_e32 v225, 0x32000, v212
	v_add_u32_e32 v226, 0x34000, v212
	v_add_u32_e32 v227, 0x36000, v212
	global_load_ushort v96, v212, s[14:15]
	global_load_ushort v97, v212, s[14:15] offset:64
	global_load_ushort v98, v212, s[14:15] offset:128
	global_load_ushort v99, v212, s[14:15] offset:192
	global_load_ushort v100, v213, s[14:15]
	global_load_ushort v101, v213, s[14:15] offset:64
	global_load_ushort v102, v213, s[14:15] offset:128
	global_load_ushort v103, v213, s[14:15] offset:192
	global_load_ushort v104, v214, s[14:15]
	global_load_ushort v105, v214, s[14:15] offset:64
	global_load_ushort v106, v214, s[14:15] offset:128
	global_load_ushort v107, v214, s[14:15] offset:192
	global_load_ushort v108, v215, s[14:15]
	global_load_ushort v109, v215, s[14:15] offset:64
	global_load_ushort v110, v215, s[14:15] offset:128
	global_load_ushort v111, v215, s[14:15] offset:192
	global_load_ushort v112, v216, s[14:15]
	global_load_ushort v113, v216, s[14:15] offset:64
	global_load_ushort v114, v216, s[14:15] offset:128
	global_load_ushort v115, v216, s[14:15] offset:192
	global_load_ushort v116, v217, s[14:15]
	global_load_ushort v117, v217, s[14:15] offset:64
	global_load_ushort v118, v217, s[14:15] offset:128
	global_load_ushort v119, v217, s[14:15] offset:192
	global_load_ushort v120, v218, s[14:15]
	global_load_ushort v121, v218, s[14:15] offset:64
	global_load_ushort v122, v218, s[14:15] offset:128
	global_load_ushort v123, v218, s[14:15] offset:192
	global_load_ushort v124, v219, s[14:15]
	global_load_ushort v125, v219, s[14:15] offset:64
	global_load_ushort v126, v219, s[14:15] offset:128
	global_load_ushort v127, v219, s[14:15] offset:192
	s_add_i32 s55, s55, 1
	v_rcp_f32_e32 v80, v80
	v_rcp_f32_e32 v81, v81
	v_rcp_f32_e32 v82, v82
	v_rcp_f32_e32 v83, v83
	v_rcp_f32_e32 v84, v84
	v_rcp_f32_e32 v85, v85
	v_rcp_f32_e32 v86, v86
	v_rcp_f32_e32 v87, v87
	v_rcp_f32_e32 v88, v88
	v_rcp_f32_e32 v89, v89
	v_rcp_f32_e32 v90, v90
	v_rcp_f32_e32 v91, v91
	v_rcp_f32_e32 v92, v92
	v_rcp_f32_e32 v93, v93
	v_rcp_f32_e32 v94, v94
	v_rcp_f32_e32 v95, v95
	s_waitcnt vmcnt(28)
	v_lshlrev_b32_e32 v96, 16, v96
	v_mul_f32_e32 v64, v64, v80
	v_mul_f32_e32 v64, v64, v96
	v_cvt_pk_bf16_f32 v64, v64, v64
	v_lshlrev_b32_e32 v97, 16, v97
	v_mul_f32_e32 v48, v48, v80
	v_mul_f32_e32 v48, v48, v97
	v_cvt_pk_bf16_f32 v48, v48, v48
	v_lshlrev_b32_e32 v98, 16, v98
	v_mul_f32_e32 v32, v32, v80
	v_mul_f32_e32 v32, v32, v98
	v_cvt_pk_bf16_f32 v32, v32, v32
	v_lshlrev_b32_e32 v99, 16, v99
	v_mul_f32_e32 v16, v16, v80
	v_mul_f32_e32 v16, v16, v99
	v_cvt_pk_bf16_f32 v16, v16, v16
	global_store_short v212, v64, s[12:13]
	global_store_short v212, v48, s[12:13] offset:64
	global_store_short v212, v32, s[12:13] offset:128
	global_store_short v212, v16, s[12:13] offset:192
	global_load_ushort v128, v220, s[14:15]
	global_load_ushort v129, v220, s[14:15] offset:64
	global_load_ushort v130, v220, s[14:15] offset:128
	global_load_ushort v131, v220, s[14:15] offset:192
	s_waitcnt vmcnt(32)
	v_lshlrev_b32_e32 v100, 16, v100
	v_mul_f32_e32 v65, v65, v81
	v_mul_f32_e32 v65, v65, v100
	v_cvt_pk_bf16_f32 v65, v65, v65
	v_lshlrev_b32_e32 v101, 16, v101
	v_mul_f32_e32 v49, v49, v81
	v_mul_f32_e32 v49, v49, v101
	v_cvt_pk_bf16_f32 v49, v49, v49
	v_lshlrev_b32_e32 v102, 16, v102
	v_mul_f32_e32 v33, v33, v81
	v_mul_f32_e32 v33, v33, v102
	v_cvt_pk_bf16_f32 v33, v33, v33
	v_lshlrev_b32_e32 v103, 16, v103
	v_mul_f32_e32 v17, v17, v81
	v_mul_f32_e32 v17, v17, v103
	v_cvt_pk_bf16_f32 v17, v17, v17
	global_store_short v213, v65, s[12:13]
	global_store_short v213, v49, s[12:13] offset:64
	global_store_short v213, v33, s[12:13] offset:128
	global_store_short v213, v17, s[12:13] offset:192
	global_load_ushort v132, v221, s[14:15]
	global_load_ushort v133, v221, s[14:15] offset:64
	global_load_ushort v134, v221, s[14:15] offset:128
	global_load_ushort v135, v221, s[14:15] offset:192
	s_waitcnt vmcnt(36)
	v_lshlrev_b32_e32 v104, 16, v104
	v_mul_f32_e32 v66, v66, v82
	v_mul_f32_e32 v66, v66, v104
	v_cvt_pk_bf16_f32 v66, v66, v66
	v_lshlrev_b32_e32 v105, 16, v105
	v_mul_f32_e32 v50, v50, v82
	v_mul_f32_e32 v50, v50, v105
	v_cvt_pk_bf16_f32 v50, v50, v50
	v_lshlrev_b32_e32 v106, 16, v106
	v_mul_f32_e32 v34, v34, v82
	v_mul_f32_e32 v34, v34, v106
	v_cvt_pk_bf16_f32 v34, v34, v34
	v_lshlrev_b32_e32 v107, 16, v107
	v_mul_f32_e32 v18, v18, v82
	v_mul_f32_e32 v18, v18, v107
	v_cvt_pk_bf16_f32 v18, v18, v18
	global_store_short v214, v66, s[12:13]
	global_store_short v214, v50, s[12:13] offset:64
	global_store_short v214, v34, s[12:13] offset:128
	global_store_short v214, v18, s[12:13] offset:192
	global_load_ushort v136, v222, s[14:15]
	global_load_ushort v137, v222, s[14:15] offset:64
	global_load_ushort v138, v222, s[14:15] offset:128
	global_load_ushort v139, v222, s[14:15] offset:192
	s_waitcnt vmcnt(40)
; __device__ __forceinline__ u16 f2bf(float f) { return (u16)(cvtpk(f, f) & 0xffffu); }
; __device__ __forceinline__ float bf2f(u16 v) { return __uint_as_float(((unsigned)v) << 16); }
; __device__ __forceinline__ int crow(int r, int hi) { return (r & 3) + 8 * (r >> 2) + 4 * hi; }
; template <int MODE>
; __device__ __forceinline__ void attn_item(const Params& P, int b, int h, int qb, char* lds) {
;     ...
; #pragma unroll
;   for (int r = 0; r < 16; ++r) {
;     const float rl = __builtin_amdgcn_rcpf(ol[r]);
;     const size_t rowoff = (size_t)(b * SEQ + q0 + crow(r, hi)) * DM + h * 128;
; #pragma unroll
;     for (int d0 = 0; d0 < 4; ++d0) {
;       const size_t idx = rowoff + d0 * 32 + r32;
;       const float v = o[d0][r] * rl * bf2f(P_gate[idx]);
;       P_og[idx] = f2bf(v);
;     }
;   }
	v_lshlrev_b32_e32 v108, 16, v108
	v_mul_f32_e32 v67, v67, v83
	v_mul_f32_e32 v67, v67, v108
	v_cvt_pk_bf16_f32 v67, v67, v67
	v_lshlrev_b32_e32 v109, 16, v109
	v_mul_f32_e32 v51, v51, v83
	v_mul_f32_e32 v51, v51, v109
	v_cvt_pk_bf16_f32 v51, v51, v51
	v_lshlrev_b32_e32 v110, 16, v110
	v_mul_f32_e32 v35, v35, v83
	v_mul_f32_e32 v35, v35, v110
	v_cvt_pk_bf16_f32 v35, v35, v35
	v_lshlrev_b32_e32 v111, 16, v111
	v_mul_f32_e32 v19, v19, v83
	v_mul_f32_e32 v19, v19, v111
	v_cvt_pk_bf16_f32 v19, v19, v19
	global_store_short v215, v67, s[12:13]
	global_store_short v215, v51, s[12:13] offset:64
	global_store_short v215, v35, s[12:13] offset:128
	global_store_short v215, v19, s[12:13] offset:192
	global_load_ushort v140, v223, s[14:15]
	global_load_ushort v141, v223, s[14:15] offset:64
	global_load_ushort v142, v223, s[14:15] offset:128
	global_load_ushort v143, v223, s[14:15] offset:192
	s_waitcnt vmcnt(44)
	v_lshlrev_b32_e32 v112, 16, v112
	v_mul_f32_e32 v68, v68, v84
	v_mul_f32_e32 v68, v68, v112
	v_cvt_pk_bf16_f32 v68, v68, v68
	v_lshlrev_b32_e32 v113, 16, v113
	v_mul_f32_e32 v52, v52, v84
	v_mul_f32_e32 v52, v52, v113
	v_cvt_pk_bf16_f32 v52, v52, v52
	v_lshlrev_b32_e32 v114, 16, v114
	v_mul_f32_e32 v36, v36, v84
	v_mul_f32_e32 v36, v36, v114
	v_cvt_pk_bf16_f32 v36, v36, v36
	v_lshlrev_b32_e32 v115, 16, v115
	v_mul_f32_e32 v20, v20, v84
	v_mul_f32_e32 v20, v20, v115
	v_cvt_pk_bf16_f32 v20, v20, v20
	global_store_short v216, v68, s[12:13]
	global_store_short v216, v52, s[12:13] offset:64
	global_store_short v216, v36, s[12:13] offset:128
	global_store_short v216, v20, s[12:13] offset:192
	global_load_ushort v144, v224, s[14:15]
	global_load_ushort v145, v224, s[14:15] offset:64
	global_load_ushort v146, v224, s[14:15] offset:128
	global_load_ushort v147, v224, s[14:15] offset:192
	s_waitcnt vmcnt(48)
	v_lshlrev_b32_e32 v116, 16, v116
	v_mul_f32_e32 v69, v69, v85
	v_mul_f32_e32 v69, v69, v116
	v_cvt_pk_bf16_f32 v69, v69, v69
	v_lshlrev_b32_e32 v117, 16, v117
	v_mul_f32_e32 v53, v53, v85
	v_mul_f32_e32 v53, v53, v117
	v_cvt_pk_bf16_f32 v53, v53, v53
	v_lshlrev_b32_e32 v118, 16, v118
	v_mul_f32_e32 v37, v37, v85
	v_mul_f32_e32 v37, v37, v118
	v_cvt_pk_bf16_f32 v37, v37, v37
	v_lshlrev_b32_e32 v119, 16, v119
	v_mul_f32_e32 v21, v21, v85
	v_mul_f32_e32 v21, v21, v119
	v_cvt_pk_bf16_f32 v21, v21, v21
	global_store_short v217, v69, s[12:13]
	global_store_short v217, v53, s[12:13] offset:64
	global_store_short v217, v37, s[12:13] offset:128
	global_store_short v217, v21, s[12:13] offset:192
	global_load_ushort v148, v225, s[14:15]
	global_load_ushort v149, v225, s[14:15] offset:64
	global_load_ushort v150, v225, s[14:15] offset:128
	global_load_ushort v151, v225, s[14:15] offset:192
	s_waitcnt vmcnt(48)
	v_lshlrev_b32_e32 v120, 16, v120
	v_mul_f32_e32 v70, v70, v86
	v_mul_f32_e32 v70, v70, v120
	v_cvt_pk_bf16_f32 v70, v70, v70
	v_lshlrev_b32_e32 v121, 16, v121
	v_mul_f32_e32 v54, v54, v86
	v_mul_f32_e32 v54, v54, v121
	v_cvt_pk_bf16_f32 v54, v54, v54
	v_lshlrev_b32_e32 v122, 16, v122
	v_mul_f32_e32 v38, v38, v86
	v_mul_f32_e32 v38, v38, v122
	v_cvt_pk_bf16_f32 v38, v38, v38
	v_lshlrev_b32_e32 v123, 16, v123
	v_mul_f32_e32 v22, v22, v86
	v_mul_f32_e32 v22, v22, v123
	v_cvt_pk_bf16_f32 v22, v22, v22
	global_store_short v218, v70, s[12:13]
	global_store_short v218, v54, s[12:13] offset:64
	global_store_short v218, v38, s[12:13] offset:128
	global_store_short v218, v22, s[12:13] offset:192
	global_load_ushort v152, v226, s[14:15]
	global_load_ushort v153, v226, s[14:15] offset:64
	global_load_ushort v154, v226, s[14:15] offset:128
	global_load_ushort v155, v226, s[14:15] offset:192
	s_waitcnt vmcnt(48)
	v_lshlrev_b32_e32 v124, 16, v124
	v_mul_f32_e32 v71, v71, v87
	v_mul_f32_e32 v71, v71, v124
	v_cvt_pk_bf16_f32 v71, v71, v71
	v_lshlrev_b32_e32 v125, 16, v125
	v_mul_f32_e32 v55, v55, v87
	v_mul_f32_e32 v55, v55, v125
	v_cvt_pk_bf16_f32 v55, v55, v55
	v_lshlrev_b32_e32 v126, 16, v126
	v_mul_f32_e32 v39, v39, v87
	v_mul_f32_e32 v39, v39, v126
	v_cvt_pk_bf16_f32 v39, v39, v39
	v_lshlrev_b32_e32 v127, 16, v127
	v_mul_f32_e32 v23, v23, v87
	v_mul_f32_e32 v23, v23, v127
	v_cvt_pk_bf16_f32 v23, v23, v23
	global_store_short v219, v71, s[12:13]
	global_store_short v219, v55, s[12:13] offset:64
	global_store_short v219, v39, s[12:13] offset:128
	global_store_short v219, v23, s[12:13] offset:192
	global_load_ushort v156, v227, s[14:15]
	global_load_ushort v157, v227, s[14:15] offset:64
	global_load_ushort v158, v227, s[14:15] offset:128
	global_load_ushort v159, v227, s[14:15] offset:192
	s_waitcnt vmcnt(48)
	v_lshlrev_b32_e32 v128, 16, v128
	v_mul_f32_e32 v72, v72, v88
	v_mul_f32_e32 v72, v72, v128
	v_cvt_pk_bf16_f32 v72, v72, v72
	v_lshlrev_b32_e32 v129, 16, v129
	v_mul_f32_e32 v56, v56, v88
	v_mul_f32_e32 v56, v56, v129
	v_cvt_pk_bf16_f32 v56, v56, v56
	v_lshlrev_b32_e32 v130, 16, v130
	v_mul_f32_e32 v40, v40, v88
	v_mul_f32_e32 v40, v40, v130
	v_cvt_pk_bf16_f32 v40, v40, v40
	v_lshlrev_b32_e32 v131, 16, v131
	v_mul_f32_e32 v24, v24, v88
	v_mul_f32_e32 v24, v24, v131
	v_cvt_pk_bf16_f32 v24, v24, v24
	global_store_short v220, v72, s[12:13]
	global_store_short v220, v56, s[12:13] offset:64
	global_store_short v220, v40, s[12:13] offset:128
	global_store_short v220, v24, s[12:13] offset:192
	s_waitcnt vmcnt(48)
; __device__ __forceinline__ u16 f2bf(float f) { return (u16)(cvtpk(f, f) & 0xffffu); }
; __device__ __forceinline__ float bf2f(u16 v) { return __uint_as_float(((unsigned)v) << 16); }
; __device__ __forceinline__ int crow(int r, int hi) { return (r & 3) + 8 * (r >> 2) + 4 * hi; }
; template <int MODE>
; __device__ __forceinline__ void attn_item(const Params& P, int b, int h, int qb, char* lds) {
;     ...
; #pragma unroll
;   for (int r = 0; r < 16; ++r) {
;     const float rl = __builtin_amdgcn_rcpf(ol[r]);
;     const size_t rowoff = (size_t)(b * SEQ + q0 + crow(r, hi)) * DM + h * 128;
; #pragma unroll
;     for (int d0 = 0; d0 < 4; ++d0) {
;       const size_t idx = rowoff + d0 * 32 + r32;
;       const float v = o[d0][r] * rl * bf2f(P_gate[idx]);
;       P_og[idx] = f2bf(v);
;     }
;   }
;   __syncthreads();
	v_lshlrev_b32_e32 v132, 16, v132
	v_mul_f32_e32 v73, v73, v89
	v_mul_f32_e32 v73, v73, v132
	v_cvt_pk_bf16_f32 v73, v73, v73
	v_lshlrev_b32_e32 v133, 16, v133
	v_mul_f32_e32 v57, v57, v89
	v_mul_f32_e32 v57, v57, v133
	v_cvt_pk_bf16_f32 v57, v57, v57
	v_lshlrev_b32_e32 v134, 16, v134
	v_mul_f32_e32 v41, v41, v89
	v_mul_f32_e32 v41, v41, v134
	v_cvt_pk_bf16_f32 v41, v41, v41
	v_lshlrev_b32_e32 v135, 16, v135
	v_mul_f32_e32 v25, v25, v89
	v_mul_f32_e32 v25, v25, v135
	v_cvt_pk_bf16_f32 v25, v25, v25
	global_store_short v221, v73, s[12:13]
	global_store_short v221, v57, s[12:13] offset:64
	global_store_short v221, v41, s[12:13] offset:128
	global_store_short v221, v25, s[12:13] offset:192
	s_waitcnt vmcnt(48)
	v_lshlrev_b32_e32 v136, 16, v136
	v_mul_f32_e32 v74, v74, v90
	v_mul_f32_e32 v74, v74, v136
	v_cvt_pk_bf16_f32 v74, v74, v74
	v_lshlrev_b32_e32 v137, 16, v137
	v_mul_f32_e32 v58, v58, v90
	v_mul_f32_e32 v58, v58, v137
	v_cvt_pk_bf16_f32 v58, v58, v58
	v_lshlrev_b32_e32 v138, 16, v138
	v_mul_f32_e32 v42, v42, v90
	v_mul_f32_e32 v42, v42, v138
	v_cvt_pk_bf16_f32 v42, v42, v42
	v_lshlrev_b32_e32 v139, 16, v139
	v_mul_f32_e32 v26, v26, v90
	v_mul_f32_e32 v26, v26, v139
	v_cvt_pk_bf16_f32 v26, v26, v26
	global_store_short v222, v74, s[12:13]
	global_store_short v222, v58, s[12:13] offset:64
	global_store_short v222, v42, s[12:13] offset:128
	global_store_short v222, v26, s[12:13] offset:192
	s_waitcnt vmcnt(44)
	v_lshlrev_b32_e32 v140, 16, v140
	v_mul_f32_e32 v75, v75, v91
	v_mul_f32_e32 v75, v75, v140
	v_cvt_pk_bf16_f32 v75, v75, v75
	v_lshlrev_b32_e32 v141, 16, v141
	v_mul_f32_e32 v59, v59, v91
	v_mul_f32_e32 v59, v59, v141
	v_cvt_pk_bf16_f32 v59, v59, v59
	v_lshlrev_b32_e32 v142, 16, v142
	v_mul_f32_e32 v43, v43, v91
	v_mul_f32_e32 v43, v43, v142
	v_cvt_pk_bf16_f32 v43, v43, v43
	v_lshlrev_b32_e32 v143, 16, v143
	v_mul_f32_e32 v27, v27, v91
	v_mul_f32_e32 v27, v27, v143
	v_cvt_pk_bf16_f32 v27, v27, v27
	global_store_short v223, v75, s[12:13]
	global_store_short v223, v59, s[12:13] offset:64
	global_store_short v223, v43, s[12:13] offset:128
	global_store_short v223, v27, s[12:13] offset:192
	s_waitcnt vmcnt(40)
	v_lshlrev_b32_e32 v144, 16, v144
	v_mul_f32_e32 v76, v76, v92
	v_mul_f32_e32 v76, v76, v144
	v_cvt_pk_bf16_f32 v76, v76, v76
	v_lshlrev_b32_e32 v145, 16, v145
	v_mul_f32_e32 v60, v60, v92
	v_mul_f32_e32 v60, v60, v145
	v_cvt_pk_bf16_f32 v60, v60, v60
	v_lshlrev_b32_e32 v146, 16, v146
	v_mul_f32_e32 v44, v44, v92
	v_mul_f32_e32 v44, v44, v146
	v_cvt_pk_bf16_f32 v44, v44, v44
	v_lshlrev_b32_e32 v147, 16, v147
	v_mul_f32_e32 v28, v28, v92
	v_mul_f32_e32 v28, v28, v147
	v_cvt_pk_bf16_f32 v28, v28, v28
	global_store_short v224, v76, s[12:13]
	global_store_short v224, v60, s[12:13] offset:64
	global_store_short v224, v44, s[12:13] offset:128
	global_store_short v224, v28, s[12:13] offset:192
	s_waitcnt vmcnt(36)
	v_lshlrev_b32_e32 v148, 16, v148
	v_mul_f32_e32 v77, v77, v93
	v_mul_f32_e32 v77, v77, v148
	v_cvt_pk_bf16_f32 v77, v77, v77
	v_lshlrev_b32_e32 v149, 16, v149
	v_mul_f32_e32 v61, v61, v93
	v_mul_f32_e32 v61, v61, v149
	v_cvt_pk_bf16_f32 v61, v61, v61
	v_lshlrev_b32_e32 v150, 16, v150
	v_mul_f32_e32 v45, v45, v93
	v_mul_f32_e32 v45, v45, v150
	v_cvt_pk_bf16_f32 v45, v45, v45
	v_lshlrev_b32_e32 v151, 16, v151
	v_mul_f32_e32 v29, v29, v93
	v_mul_f32_e32 v29, v29, v151
	v_cvt_pk_bf16_f32 v29, v29, v29
	global_store_short v225, v77, s[12:13]
	global_store_short v225, v61, s[12:13] offset:64
	global_store_short v225, v45, s[12:13] offset:128
	global_store_short v225, v29, s[12:13] offset:192
	s_waitcnt vmcnt(32)
	v_lshlrev_b32_e32 v152, 16, v152
	v_mul_f32_e32 v78, v78, v94
	v_mul_f32_e32 v78, v78, v152
	v_cvt_pk_bf16_f32 v78, v78, v78
	v_lshlrev_b32_e32 v153, 16, v153
	v_mul_f32_e32 v62, v62, v94
	v_mul_f32_e32 v62, v62, v153
	v_cvt_pk_bf16_f32 v62, v62, v62
	v_lshlrev_b32_e32 v154, 16, v154
	v_mul_f32_e32 v46, v46, v94
	v_mul_f32_e32 v46, v46, v154
	v_cvt_pk_bf16_f32 v46, v46, v46
	v_lshlrev_b32_e32 v155, 16, v155
	v_mul_f32_e32 v30, v30, v94
	v_mul_f32_e32 v30, v30, v155
	v_cvt_pk_bf16_f32 v30, v30, v30
	global_store_short v226, v78, s[12:13]
	global_store_short v226, v62, s[12:13] offset:64
	global_store_short v226, v46, s[12:13] offset:128
	global_store_short v226, v30, s[12:13] offset:192
	s_waitcnt vmcnt(28)
	v_lshlrev_b32_e32 v156, 16, v156
	v_mul_f32_e32 v79, v79, v95
	v_mul_f32_e32 v79, v79, v156
	v_cvt_pk_bf16_f32 v79, v79, v79
	v_lshlrev_b32_e32 v157, 16, v157
	v_mul_f32_e32 v63, v63, v95
	v_mul_f32_e32 v63, v63, v157
	v_cvt_pk_bf16_f32 v63, v63, v63
	v_lshlrev_b32_e32 v158, 16, v158
	v_mul_f32_e32 v47, v47, v95
	v_mul_f32_e32 v47, v47, v158
	v_cvt_pk_bf16_f32 v47, v47, v47
	v_lshlrev_b32_e32 v159, 16, v159
	v_mul_f32_e32 v31, v31, v95
	v_mul_f32_e32 v31, v31, v159
	v_cvt_pk_bf16_f32 v31, v31, v31
	global_store_short v227, v79, s[12:13]
	global_store_short v227, v63, s[12:13] offset:64
	global_store_short v227, v47, s[12:13] offset:128
	global_store_short v227, v31, s[12:13] offset:192
	s_cmp_eq_u32 s55, 4
	s_barrier
	s_cbranch_scc1 .LBB0_676

; __device__ __forceinline__ u16 f2bf(float f) { return (u16)(cvtpk(f, f) & 0xffffu); }
; __device__ __forceinline__ float bf2f(u16 v) { return __uint_as_float(((unsigned)v) << 16); }
; __device__ __forceinline__ int crow(int r, int hi) { return (r & 3) + 8 * (r >> 2) + 4 * hi; }
; template <int MODE>
; __device__ __forceinline__ void attn_item(const Params& P, int b, int h, int qb, char* lds) {
;     ...
; #pragma unroll
;   for (int r = 0; r < 16; ++r) {
;     const float rl = __builtin_amdgcn_rcpf(ol[r]);
;     const size_t rowoff = (size_t)(b * SEQ + q0 + crow(r, hi)) * DM + h * 128;
; #pragma unroll
;     for (int d0 = 0; d0 < 4; ++d0) {
;       const size_t idx = rowoff + d0 * 32 + r32;
;       const float v = o[d0][r] * rl * bf2f(P_gate[idx]);
;       P_og[idx] = f2bf(v);
;     }
;   }
.LBB0_1008:
	s_lshl_b32 s0, s34, 7
	s_and_b32 s2, s0, 0xfffff000
	s_add_i32 s71, s71, s2
	v_or_b32_e32 v2, s71, v175
	s_and_b32 s0, s0, 0xf80
	v_or_b32_e32 v0, s0, v172
	v_lshlrev_b32_e32 v2, 12, v2
	v_add_lshl_u32 v194, v2, v0, 1
	v_add_u32_e32 v195, 0x2000, v194
	v_add_u32_e32 v196, 0x4000, v194
	v_add_u32_e32 v197, 0x6000, v194
	v_add_u32_e32 v198, 0x10000, v194
	v_add_u32_e32 v199, 0x12000, v194
	v_add_u32_e32 v200, 0x14000, v194
	v_add_u32_e32 v201, 0x16000, v194
	v_add_u32_e32 v202, 0x20000, v194
	v_add_u32_e32 v203, 0x22000, v194
	v_add_u32_e32 v204, 0x24000, v194
	v_add_u32_e32 v205, 0x26000, v194
	v_add_u32_e32 v206, 0x30000, v194
	v_add_u32_e32 v207, 0x32000, v194
	v_add_u32_e32 v208, 0x34000, v194
	v_add_u32_e32 v209, 0x36000, v194
	global_load_ushort v96, v194, s[14:15]
	global_load_ushort v97, v194, s[14:15] offset:64
	global_load_ushort v98, v194, s[14:15] offset:128
	global_load_ushort v99, v194, s[14:15] offset:192
	global_load_ushort v100, v195, s[14:15]
	global_load_ushort v101, v195, s[14:15] offset:64
	global_load_ushort v102, v195, s[14:15] offset:128
	global_load_ushort v103, v195, s[14:15] offset:192
	global_load_ushort v104, v196, s[14:15]
	global_load_ushort v105, v196, s[14:15] offset:64
	global_load_ushort v106, v196, s[14:15] offset:128
	global_load_ushort v107, v196, s[14:15] offset:192
	global_load_ushort v108, v197, s[14:15]
	global_load_ushort v109, v197, s[14:15] offset:64
	global_load_ushort v110, v197, s[14:15] offset:128
	global_load_ushort v111, v197, s[14:15] offset:192
	global_load_ushort v112, v198, s[14:15]
	global_load_ushort v113, v198, s[14:15] offset:64
	global_load_ushort v114, v198, s[14:15] offset:128
	global_load_ushort v115, v198, s[14:15] offset:192
	global_load_ushort v116, v199, s[14:15]
	global_load_ushort v117, v199, s[14:15] offset:64
	global_load_ushort v118, v199, s[14:15] offset:128
	global_load_ushort v119, v199, s[14:15] offset:192
	global_load_ushort v120, v200, s[14:15]
	global_load_ushort v121, v200, s[14:15] offset:64
	global_load_ushort v122, v200, s[14:15] offset:128
	global_load_ushort v123, v200, s[14:15] offset:192
	global_load_ushort v124, v201, s[14:15]
	global_load_ushort v125, v201, s[14:15] offset:64
	global_load_ushort v126, v201, s[14:15] offset:128
	global_load_ushort v127, v201, s[14:15] offset:192
	v_rcp_f32_e32 v80, v80
	v_rcp_f32_e32 v81, v81
	v_rcp_f32_e32 v82, v82
	v_rcp_f32_e32 v83, v83
	v_rcp_f32_e32 v84, v84
	v_rcp_f32_e32 v85, v85
	v_rcp_f32_e32 v86, v86
	v_rcp_f32_e32 v87, v87
	v_rcp_f32_e32 v88, v88
	v_rcp_f32_e32 v89, v89
	v_rcp_f32_e32 v90, v90
	v_rcp_f32_e32 v91, v91
	v_rcp_f32_e32 v92, v92
	v_rcp_f32_e32 v93, v93
	v_rcp_f32_e32 v94, v94
	v_rcp_f32_e32 v95, v95
	s_waitcnt vmcnt(28)
	v_lshlrev_b32_e32 v96, 16, v96
	v_mul_f32_e32 v64, v64, v80
	v_mul_f32_e32 v64, v64, v96
	v_cvt_pk_bf16_f32 v64, v64, v64
	v_lshlrev_b32_e32 v97, 16, v97
	v_mul_f32_e32 v48, v48, v80
	v_mul_f32_e32 v48, v48, v97
	v_cvt_pk_bf16_f32 v48, v48, v48
	v_lshlrev_b32_e32 v98, 16, v98
	v_mul_f32_e32 v32, v32, v80
	v_mul_f32_e32 v32, v32, v98
	v_cvt_pk_bf16_f32 v32, v32, v32
	v_lshlrev_b32_e32 v99, 16, v99
	v_mul_f32_e32 v16, v16, v80
	v_mul_f32_e32 v16, v16, v99
	v_cvt_pk_bf16_f32 v16, v16, v16
	global_store_short v194, v64, s[12:13]
	global_store_short v194, v48, s[12:13] offset:64
	global_store_short v194, v32, s[12:13] offset:128
	global_store_short v194, v16, s[12:13] offset:192
	global_load_ushort v128, v202, s[14:15]
	global_load_ushort v129, v202, s[14:15] offset:64
	global_load_ushort v130, v202, s[14:15] offset:128
	global_load_ushort v131, v202, s[14:15] offset:192
	s_waitcnt vmcnt(32)
	v_lshlrev_b32_e32 v100, 16, v100
	v_mul_f32_e32 v65, v65, v81
	v_mul_f32_e32 v65, v65, v100
	v_cvt_pk_bf16_f32 v65, v65, v65
	v_lshlrev_b32_e32 v101, 16, v101
	v_mul_f32_e32 v49, v49, v81
	v_mul_f32_e32 v49, v49, v101
	v_cvt_pk_bf16_f32 v49, v49, v49
	v_lshlrev_b32_e32 v102, 16, v102
	v_mul_f32_e32 v33, v33, v81
	v_mul_f32_e32 v33, v33, v102
	v_cvt_pk_bf16_f32 v33, v33, v33
	v_lshlrev_b32_e32 v103, 16, v103
	v_mul_f32_e32 v17, v17, v81
	v_mul_f32_e32 v17, v17, v103
	v_cvt_pk_bf16_f32 v17, v17, v17
	global_store_short v195, v65, s[12:13]
	global_store_short v195, v49, s[12:13] offset:64
	global_store_short v195, v33, s[12:13] offset:128
	global_store_short v195, v17, s[12:13] offset:192
	global_load_ushort v132, v203, s[14:15]
	global_load_ushort v133, v203, s[14:15] offset:64
	global_load_ushort v134, v203, s[14:15] offset:128
	global_load_ushort v135, v203, s[14:15] offset:192
	s_waitcnt vmcnt(36)
	v_lshlrev_b32_e32 v104, 16, v104
	v_mul_f32_e32 v66, v66, v82
	v_mul_f32_e32 v66, v66, v104
	v_cvt_pk_bf16_f32 v66, v66, v66
	v_lshlrev_b32_e32 v105, 16, v105
	v_mul_f32_e32 v50, v50, v82
	v_mul_f32_e32 v50, v50, v105
	v_cvt_pk_bf16_f32 v50, v50, v50
	v_lshlrev_b32_e32 v106, 16, v106
	v_mul_f32_e32 v34, v34, v82
	v_mul_f32_e32 v34, v34, v106
	v_cvt_pk_bf16_f32 v34, v34, v34
	v_lshlrev_b32_e32 v107, 16, v107
	v_mul_f32_e32 v18, v18, v82
	v_mul_f32_e32 v18, v18, v107
	v_cvt_pk_bf16_f32 v18, v18, v18
	global_store_short v196, v66, s[12:13]
	global_store_short v196, v50, s[12:13] offset:64
	global_store_short v196, v34, s[12:13] offset:128
	global_store_short v196, v18, s[12:13] offset:192
	global_load_ushort v136, v204, s[14:15]
	global_load_ushort v137, v204, s[14:15] offset:64
	global_load_ushort v138, v204, s[14:15] offset:128
	global_load_ushort v139, v204, s[14:15] offset:192
	s_waitcnt vmcnt(40)
; __device__ __forceinline__ u16 f2bf(float f) { return (u16)(cvtpk(f, f) & 0xffffu); }
; __device__ __forceinline__ float bf2f(u16 v) { return __uint_as_float(((unsigned)v) << 16); }
; __device__ __forceinline__ int crow(int r, int hi) { return (r & 3) + 8 * (r >> 2) + 4 * hi; }
; template <int MODE>
; __device__ __forceinline__ void attn_item(const Params& P, int b, int h, int qb, char* lds) {
;     ...
; #pragma unroll
;   for (int r = 0; r < 16; ++r) {
;     const float rl = __builtin_amdgcn_rcpf(ol[r]);
;     const size_t rowoff = (size_t)(b * SEQ + q0 + crow(r, hi)) * DM + h * 128;
; #pragma unroll
;     for (int d0 = 0; d0 < 4; ++d0) {
;       const size_t idx = rowoff + d0 * 32 + r32;
;       const float v = o[d0][r] * rl * bf2f(P_gate[idx]);
;       P_og[idx] = f2bf(v);
;     }
;   }
	v_lshlrev_b32_e32 v108, 16, v108
	v_mul_f32_e32 v67, v67, v83
	v_mul_f32_e32 v67, v67, v108
	v_cvt_pk_bf16_f32 v67, v67, v67
	v_lshlrev_b32_e32 v109, 16, v109
	v_mul_f32_e32 v51, v51, v83
	v_mul_f32_e32 v51, v51, v109
	v_cvt_pk_bf16_f32 v51, v51, v51
	v_lshlrev_b32_e32 v110, 16, v110
	v_mul_f32_e32 v35, v35, v83
	v_mul_f32_e32 v35, v35, v110
	v_cvt_pk_bf16_f32 v35, v35, v35
	v_lshlrev_b32_e32 v111, 16, v111
	v_mul_f32_e32 v19, v19, v83
	v_mul_f32_e32 v19, v19, v111
	v_cvt_pk_bf16_f32 v19, v19, v19
	global_store_short v197, v67, s[12:13]
	global_store_short v197, v51, s[12:13] offset:64
	global_store_short v197, v35, s[12:13] offset:128
	global_store_short v197, v19, s[12:13] offset:192
	global_load_ushort v140, v205, s[14:15]
	global_load_ushort v141, v205, s[14:15] offset:64
	global_load_ushort v142, v205, s[14:15] offset:128
	global_load_ushort v143, v205, s[14:15] offset:192
	s_waitcnt vmcnt(44)
	v_lshlrev_b32_e32 v112, 16, v112
	v_mul_f32_e32 v68, v68, v84
	v_mul_f32_e32 v68, v68, v112
	v_cvt_pk_bf16_f32 v68, v68, v68
	v_lshlrev_b32_e32 v113, 16, v113
	v_mul_f32_e32 v52, v52, v84
	v_mul_f32_e32 v52, v52, v113
	v_cvt_pk_bf16_f32 v52, v52, v52
	v_lshlrev_b32_e32 v114, 16, v114
	v_mul_f32_e32 v36, v36, v84
	v_mul_f32_e32 v36, v36, v114
	v_cvt_pk_bf16_f32 v36, v36, v36
	v_lshlrev_b32_e32 v115, 16, v115
	v_mul_f32_e32 v20, v20, v84
	v_mul_f32_e32 v20, v20, v115
	v_cvt_pk_bf16_f32 v20, v20, v20
	global_store_short v198, v68, s[12:13]
	global_store_short v198, v52, s[12:13] offset:64
	global_store_short v198, v36, s[12:13] offset:128
	global_store_short v198, v20, s[12:13] offset:192
	global_load_ushort v144, v206, s[14:15]
	global_load_ushort v145, v206, s[14:15] offset:64
	global_load_ushort v146, v206, s[14:15] offset:128
	global_load_ushort v147, v206, s[14:15] offset:192
	s_waitcnt vmcnt(48)
	v_lshlrev_b32_e32 v116, 16, v116
	v_mul_f32_e32 v69, v69, v85
	v_mul_f32_e32 v69, v69, v116
	v_cvt_pk_bf16_f32 v69, v69, v69
	v_lshlrev_b32_e32 v117, 16, v117
	v_mul_f32_e32 v53, v53, v85
	v_mul_f32_e32 v53, v53, v117
	v_cvt_pk_bf16_f32 v53, v53, v53
	v_lshlrev_b32_e32 v118, 16, v118
	v_mul_f32_e32 v37, v37, v85
	v_mul_f32_e32 v37, v37, v118
	v_cvt_pk_bf16_f32 v37, v37, v37
	v_lshlrev_b32_e32 v119, 16, v119
	v_mul_f32_e32 v21, v21, v85
	v_mul_f32_e32 v21, v21, v119
	v_cvt_pk_bf16_f32 v21, v21, v21
	global_store_short v199, v69, s[12:13]
	global_store_short v199, v53, s[12:13] offset:64
	global_store_short v199, v37, s[12:13] offset:128
	global_store_short v199, v21, s[12:13] offset:192
	global_load_ushort v148, v207, s[14:15]
	global_load_ushort v149, v207, s[14:15] offset:64
	global_load_ushort v150, v207, s[14:15] offset:128
	global_load_ushort v151, v207, s[14:15] offset:192
	s_waitcnt vmcnt(48)
	v_lshlrev_b32_e32 v120, 16, v120
	v_mul_f32_e32 v70, v70, v86
	v_mul_f32_e32 v70, v70, v120
	v_cvt_pk_bf16_f32 v70, v70, v70
	v_lshlrev_b32_e32 v121, 16, v121
	v_mul_f32_e32 v54, v54, v86
	v_mul_f32_e32 v54, v54, v121
	v_cvt_pk_bf16_f32 v54, v54, v54
	v_lshlrev_b32_e32 v122, 16, v122
	v_mul_f32_e32 v38, v38, v86
	v_mul_f32_e32 v38, v38, v122
	v_cvt_pk_bf16_f32 v38, v38, v38
	v_lshlrev_b32_e32 v123, 16, v123
	v_mul_f32_e32 v22, v22, v86
	v_mul_f32_e32 v22, v22, v123
	v_cvt_pk_bf16_f32 v22, v22, v22
	global_store_short v200, v70, s[12:13]
	global_store_short v200, v54, s[12:13] offset:64
	global_store_short v200, v38, s[12:13] offset:128
	global_store_short v200, v22, s[12:13] offset:192
	global_load_ushort v152, v208, s[14:15]
	global_load_ushort v153, v208, s[14:15] offset:64
	global_load_ushort v154, v208, s[14:15] offset:128
	global_load_ushort v155, v208, s[14:15] offset:192
	s_waitcnt vmcnt(48)
	v_lshlrev_b32_e32 v124, 16, v124
	v_mul_f32_e32 v71, v71, v87
	v_mul_f32_e32 v71, v71, v124
	v_cvt_pk_bf16_f32 v71, v71, v71
	v_lshlrev_b32_e32 v125, 16, v125
	v_mul_f32_e32 v55, v55, v87
	v_mul_f32_e32 v55, v55, v125
	v_cvt_pk_bf16_f32 v55, v55, v55
	v_lshlrev_b32_e32 v126, 16, v126
	v_mul_f32_e32 v39, v39, v87
	v_mul_f32_e32 v39, v39, v126
	v_cvt_pk_bf16_f32 v39, v39, v39
	v_lshlrev_b32_e32 v127, 16, v127
	v_mul_f32_e32 v23, v23, v87
	v_mul_f32_e32 v23, v23, v127
	v_cvt_pk_bf16_f32 v23, v23, v23
	global_store_short v201, v71, s[12:13]
	global_store_short v201, v55, s[12:13] offset:64
	global_store_short v201, v39, s[12:13] offset:128
	global_store_short v201, v23, s[12:13] offset:192
	global_load_ushort v156, v209, s[14:15]
	global_load_ushort v157, v209, s[14:15] offset:64
	global_load_ushort v158, v209, s[14:15] offset:128
	global_load_ushort v159, v209, s[14:15] offset:192
	s_waitcnt vmcnt(48)
	v_lshlrev_b32_e32 v128, 16, v128
	v_mul_f32_e32 v72, v72, v88
	v_mul_f32_e32 v72, v72, v128
	v_cvt_pk_bf16_f32 v72, v72, v72
	v_lshlrev_b32_e32 v129, 16, v129
	v_mul_f32_e32 v56, v56, v88
	v_mul_f32_e32 v56, v56, v129
	v_cvt_pk_bf16_f32 v56, v56, v56
	v_lshlrev_b32_e32 v130, 16, v130
	v_mul_f32_e32 v40, v40, v88
	v_mul_f32_e32 v40, v40, v130
	v_cvt_pk_bf16_f32 v40, v40, v40
	v_lshlrev_b32_e32 v131, 16, v131
	v_mul_f32_e32 v24, v24, v88
	v_mul_f32_e32 v24, v24, v131
	v_cvt_pk_bf16_f32 v24, v24, v24
	global_store_short v202, v72, s[12:13]
	global_store_short v202, v56, s[12:13] offset:64
	global_store_short v202, v40, s[12:13] offset:128
	global_store_short v202, v24, s[12:13] offset:192
	s_waitcnt vmcnt(48)
; __device__ __forceinline__ u16 f2bf(float f) { return (u16)(cvtpk(f, f) & 0xffffu); }
; __device__ __forceinline__ float bf2f(u16 v) { return __uint_as_float(((unsigned)v) << 16); }
; __device__ __forceinline__ int crow(int r, int hi) { return (r & 3) + 8 * (r >> 2) + 4 * hi; }
; template <int MODE>
; __device__ __forceinline__ void attn_item(const Params& P, int b, int h, int qb, char* lds) {
;     ...
; #pragma unroll
;   for (int r = 0; r < 16; ++r) {
;     const float rl = __builtin_amdgcn_rcpf(ol[r]);
;     const size_t rowoff = (size_t)(b * SEQ + q0 + crow(r, hi)) * DM + h * 128;
; #pragma unroll
;     for (int d0 = 0; d0 < 4; ++d0) {
;       const size_t idx = rowoff + d0 * 32 + r32;
;       const float v = o[d0][r] * rl * bf2f(P_gate[idx]);
;       P_og[idx] = f2bf(v);
;     }
;   }
;   __syncthreads();
	v_lshlrev_b32_e32 v132, 16, v132
	v_mul_f32_e32 v73, v73, v89
	v_mul_f32_e32 v73, v73, v132
	v_cvt_pk_bf16_f32 v73, v73, v73
	v_lshlrev_b32_e32 v133, 16, v133
	v_mul_f32_e32 v57, v57, v89
	v_mul_f32_e32 v57, v57, v133
	v_cvt_pk_bf16_f32 v57, v57, v57
	v_lshlrev_b32_e32 v134, 16, v134
	v_mul_f32_e32 v41, v41, v89
	v_mul_f32_e32 v41, v41, v134
	v_cvt_pk_bf16_f32 v41, v41, v41
	v_lshlrev_b32_e32 v135, 16, v135
	v_mul_f32_e32 v25, v25, v89
	v_mul_f32_e32 v25, v25, v135
	v_cvt_pk_bf16_f32 v25, v25, v25
	global_store_short v203, v73, s[12:13]
	global_store_short v203, v57, s[12:13] offset:64
	global_store_short v203, v41, s[12:13] offset:128
	global_store_short v203, v25, s[12:13] offset:192
	s_waitcnt vmcnt(48)
	v_lshlrev_b32_e32 v136, 16, v136
	v_mul_f32_e32 v74, v74, v90
	v_mul_f32_e32 v74, v74, v136
	v_cvt_pk_bf16_f32 v74, v74, v74
	v_lshlrev_b32_e32 v137, 16, v137
	v_mul_f32_e32 v58, v58, v90
	v_mul_f32_e32 v58, v58, v137
	v_cvt_pk_bf16_f32 v58, v58, v58
	v_lshlrev_b32_e32 v138, 16, v138
	v_mul_f32_e32 v42, v42, v90
	v_mul_f32_e32 v42, v42, v138
	v_cvt_pk_bf16_f32 v42, v42, v42
	v_lshlrev_b32_e32 v139, 16, v139
	v_mul_f32_e32 v26, v26, v90
	v_mul_f32_e32 v26, v26, v139
	v_cvt_pk_bf16_f32 v26, v26, v26
	global_store_short v204, v74, s[12:13]
	global_store_short v204, v58, s[12:13] offset:64
	global_store_short v204, v42, s[12:13] offset:128
	global_store_short v204, v26, s[12:13] offset:192
	s_waitcnt vmcnt(44)
	v_lshlrev_b32_e32 v140, 16, v140
	v_mul_f32_e32 v75, v75, v91
	v_mul_f32_e32 v75, v75, v140
	v_cvt_pk_bf16_f32 v75, v75, v75
	v_lshlrev_b32_e32 v141, 16, v141
	v_mul_f32_e32 v59, v59, v91
	v_mul_f32_e32 v59, v59, v141
	v_cvt_pk_bf16_f32 v59, v59, v59
	v_lshlrev_b32_e32 v142, 16, v142
	v_mul_f32_e32 v43, v43, v91
	v_mul_f32_e32 v43, v43, v142
	v_cvt_pk_bf16_f32 v43, v43, v43
	v_lshlrev_b32_e32 v143, 16, v143
	v_mul_f32_e32 v27, v27, v91
	v_mul_f32_e32 v27, v27, v143
	v_cvt_pk_bf16_f32 v27, v27, v27
	global_store_short v205, v75, s[12:13]
	global_store_short v205, v59, s[12:13] offset:64
	global_store_short v205, v43, s[12:13] offset:128
	global_store_short v205, v27, s[12:13] offset:192
	s_waitcnt vmcnt(40)
	v_lshlrev_b32_e32 v144, 16, v144
	v_mul_f32_e32 v76, v76, v92
	v_mul_f32_e32 v76, v76, v144
	v_cvt_pk_bf16_f32 v76, v76, v76
	v_lshlrev_b32_e32 v145, 16, v145
	v_mul_f32_e32 v60, v60, v92
	v_mul_f32_e32 v60, v60, v145
	v_cvt_pk_bf16_f32 v60, v60, v60
	v_lshlrev_b32_e32 v146, 16, v146
	v_mul_f32_e32 v44, v44, v92
	v_mul_f32_e32 v44, v44, v146
	v_cvt_pk_bf16_f32 v44, v44, v44
	v_lshlrev_b32_e32 v147, 16, v147
	v_mul_f32_e32 v28, v28, v92
	v_mul_f32_e32 v28, v28, v147
	v_cvt_pk_bf16_f32 v28, v28, v28
	global_store_short v206, v76, s[12:13]
	global_store_short v206, v60, s[12:13] offset:64
	global_store_short v206, v44, s[12:13] offset:128
	global_store_short v206, v28, s[12:13] offset:192
	s_waitcnt vmcnt(36)
	v_lshlrev_b32_e32 v148, 16, v148
	v_mul_f32_e32 v77, v77, v93
	v_mul_f32_e32 v77, v77, v148
	v_cvt_pk_bf16_f32 v77, v77, v77
	v_lshlrev_b32_e32 v149, 16, v149
	v_mul_f32_e32 v61, v61, v93
	v_mul_f32_e32 v61, v61, v149
	v_cvt_pk_bf16_f32 v61, v61, v61
	v_lshlrev_b32_e32 v150, 16, v150
	v_mul_f32_e32 v45, v45, v93
	v_mul_f32_e32 v45, v45, v150
	v_cvt_pk_bf16_f32 v45, v45, v45
	v_lshlrev_b32_e32 v151, 16, v151
	v_mul_f32_e32 v29, v29, v93
	v_mul_f32_e32 v29, v29, v151
	v_cvt_pk_bf16_f32 v29, v29, v29
	global_store_short v207, v77, s[12:13]
	global_store_short v207, v61, s[12:13] offset:64
	global_store_short v207, v45, s[12:13] offset:128
	global_store_short v207, v29, s[12:13] offset:192
	s_waitcnt vmcnt(32)
	v_lshlrev_b32_e32 v152, 16, v152
	v_mul_f32_e32 v78, v78, v94
	v_mul_f32_e32 v78, v78, v152
	v_cvt_pk_bf16_f32 v78, v78, v78
	v_lshlrev_b32_e32 v153, 16, v153
	v_mul_f32_e32 v62, v62, v94
	v_mul_f32_e32 v62, v62, v153
	v_cvt_pk_bf16_f32 v62, v62, v62
	v_lshlrev_b32_e32 v154, 16, v154
	v_mul_f32_e32 v46, v46, v94
	v_mul_f32_e32 v46, v46, v154
	v_cvt_pk_bf16_f32 v46, v46, v46
	v_lshlrev_b32_e32 v155, 16, v155
	v_mul_f32_e32 v30, v30, v94
	v_mul_f32_e32 v30, v30, v155
	v_cvt_pk_bf16_f32 v30, v30, v30
	global_store_short v208, v78, s[12:13]
	global_store_short v208, v62, s[12:13] offset:64
	global_store_short v208, v46, s[12:13] offset:128
	global_store_short v208, v30, s[12:13] offset:192
	s_waitcnt vmcnt(28)
	v_lshlrev_b32_e32 v156, 16, v156
	v_mul_f32_e32 v79, v79, v95
	v_mul_f32_e32 v79, v79, v156
	v_cvt_pk_bf16_f32 v79, v79, v79
	v_lshlrev_b32_e32 v157, 16, v157
	v_mul_f32_e32 v63, v63, v95
	v_mul_f32_e32 v63, v63, v157
	v_cvt_pk_bf16_f32 v63, v63, v63
	v_lshlrev_b32_e32 v158, 16, v158
	v_mul_f32_e32 v47, v47, v95
	v_mul_f32_e32 v47, v47, v158
	v_cvt_pk_bf16_f32 v47, v47, v47
	v_lshlrev_b32_e32 v159, 16, v159
	v_mul_f32_e32 v31, v31, v95
	v_mul_f32_e32 v31, v31, v159
	v_cvt_pk_bf16_f32 v31, v31, v31
	global_store_short v209, v79, s[12:13]
	global_store_short v209, v63, s[12:13] offset:64
	global_store_short v209, v47, s[12:13] offset:128
	global_store_short v209, v31, s[12:13] offset:192
	s_add_i32 s70, s70, 1
	s_add_u32 s67, s67, 0x8000
	s_addc_u32 s69, s69, 0
	s_add_u32 s30, s30, 0x200000
	s_addc_u32 s31, s31, 0
	s_cmp_eq_u32 s70, 4
	s_waitcnt lgkmcnt(0)
	s_barrier
	s_cbranch_scc1 .LBB0_1006
